# cross-attention softmax: exp argument formed with one fma (s*log2e - m*log2e) instead of sub + mul
# speedup vs baseline: 1.0078x; 1.0041x over previous
; #define LAS __attribute__((address_space(3)))
; __device__ __forceinline__ unsigned pk2(float lo, float hi) { return pg8::cvt_pk_bf16(lo, hi); }
; __device__ __forceinline__ float row_rs(const float* ssq, int row) { return ssq ? rsqrtf(ssq[row] * (1.f / 1024.f) + RMS_EPS) : 1.f; }
;     __device__ __forceinline__ void fused(f32x4 (&acc)[2][2][4][2], const pg8::Unit& u, int wr, int wc, int fr, int fq, LAS unsigned char* lds, int wid, int lane) const {
;         LAS bf16* QI = (LAS bf16*)lds;
; #pragma unroll
;         for (int ai = 0; ai < 2; ++ai)
; #pragma unroll
;             for (int m = 0; m < 4; ++m) { const int rl = ai * 128 + wr * 64 + m * 16 + fr; const float rs = pg8::row_rs(ssq, u.pm * 256 + rl);
; #pragma unroll
;                 for (int bj = 0; bj < 2; ++bj)
; #pragma unroll
;                     for (int n = 0; n < 2; ++n) { const f32x4 v = acc[ai][bj][m][n] * rs; v2u w; w.x = pk2(v[0], v[1]); w.y = pk2(v[2], v[3]);
;                         *(LAS v2u*)(QI + rl * XP + bj * 128 + wc * 32 + n * 16 + 4 * fq) = w; } }
.LBB0_1108:
	s_add_u32 s4, s48, 0x20000
	s_addc_u32 s5, s49, 0
	v_lshrrev_b32_e32 v128, 5, v208
	s_lshl_b32 s13, s10, 8
	v_lshlrev_b32_e32 v189, 4, v128
	v_lshlrev_b32_e32 v211, 2, v128
	v_add_u32_e32 v128, s13, v146
	v_ashrrev_i32_e32 v129, 31, v128
	v_lshl_add_u64 v[132:133], v[128:129], 2, s[4:5]
	s_barrier
	global_load_dword v131, v[132:133], off
	global_load_dword v136, v[132:133], off offset:64
	global_load_dword v137, v[132:133], off offset:128
	global_load_dword v138, v[132:133], off offset:192
	global_load_dword v139, v[132:133], off offset:512
	global_load_dword v140, v[132:133], off offset:576
	global_load_dword v141, v[132:133], off offset:640
	global_load_dword v142, v[132:133], off offset:704
	s_lshl_b32 s6, s39, 6
	v_mov_b32_e32 v129, 0x358637bd
	s_add_i32 s7, s6, 0
	s_mov_b32 s6, 0x800000
	s_movk_i32 s14, 0x210
	s_ashr_i32 s15, s10, 4
	s_add_i32 s12, 0, 0x10800
	s_andn2_b32 s30, s30, 63
	v_and_b32_e32 v210, 31, v209
	v_and_b32_e32 v188, 8, v147
	v_and_b32_e32 v190, 0x1f0, v144
	v_lshl_or_b32 v214, s31, 5, v210
	v_mov_b32_e32 v191, 0
	v_lshlrev_b32_e32 v130, 1, v188
	v_add_u32_e32 v216, 0, v190
	v_add_u32_e32 v215, s12, v190
	v_mul_u32_u24_e32 v212, 0x210, v210
	v_add3_u32 v213, 0, v212, v189
	s_mov_b32 s11, 0
	s_waitcnt vmcnt(0)
	v_fmamk_f32 v131, v131, 0x3a800000, v129
	s_nop 0
	v_rsq_f32_e32 v131, v131
	s_nop 0
	v_mov_b32_e32 v132, v131
	v_mul_lo_u32 v131, v146, s14
	v_pk_mul_f32 v[118:119], v[118:119], v[132:133] op_sel_hi:[1,0]
	v_pk_mul_f32 v[116:117], v[116:117], v[132:133] op_sel_hi:[1,0]
	v_pk_mul_f32 v[114:115], v[114:115], v[132:133] op_sel_hi:[1,0]
	v_pk_mul_f32 v[112:113], v[112:113], v[132:133] op_sel_hi:[1,0]
	v_add3_u32 v131, s7, v145, v131
	v_cvt_pk_bf16_f32 v116, v116, v117
	v_cvt_pk_bf16_f32 v117, v118, v119
	v_cvt_pk_bf16_f32 v112, v112, v113
	v_cvt_pk_bf16_f32 v113, v114, v115
	ds_write2_b64 v131, v[116:117], v[112:113] offset0:32 offset1:36
	v_pk_mul_f32 v[126:127], v[126:127], v[132:133] op_sel_hi:[1,0]
	v_pk_mul_f32 v[124:125], v[124:125], v[132:133] op_sel_hi:[1,0]
	v_pk_mul_f32 v[122:123], v[122:123], v[132:133] op_sel_hi:[1,0]
	v_pk_mul_f32 v[120:121], v[120:121], v[132:133] op_sel_hi:[1,0]
	v_cvt_pk_bf16_f32 v124, v124, v125
	v_cvt_pk_bf16_f32 v125, v126, v127
	v_cvt_pk_bf16_f32 v120, v120, v121
	v_cvt_pk_bf16_f32 v121, v122, v123
	ds_write2_b64 v131, v[124:125], v[120:121] offset1:4
	s_waitcnt vmcnt(0)
	v_fmamk_f32 v112, v136, 0x3a800000, v129
	s_nop 0
	v_rsq_f32_e32 v112, v112
	s_nop 0
	v_add_u32_e32 v113, 0x2100, v131
	v_pk_mul_f32 v[106:107], v[106:107], v[112:113] op_sel_hi:[1,0]
	v_pk_mul_f32 v[104:105], v[104:105], v[112:113] op_sel_hi:[1,0]
	v_pk_mul_f32 v[102:103], v[102:103], v[112:113] op_sel_hi:[1,0]
	v_pk_mul_f32 v[100:101], v[100:101], v[112:113] op_sel_hi:[1,0]
	v_pk_mul_f32 v[98:99], v[98:99], v[112:113] op_sel_hi:[1,0]
	v_pk_mul_f32 v[96:97], v[96:97], v[112:113] op_sel_hi:[1,0]
	v_cvt_pk_bf16_f32 v104, v104, v105
	v_cvt_pk_bf16_f32 v105, v106, v107
	v_add_u32_e32 v106, 0x2000, v131
	v_cvt_pk_bf16_f32 v100, v100, v101
	v_cvt_pk_bf16_f32 v101, v102, v103
	v_cvt_pk_bf16_f32 v96, v96, v97
	v_cvt_pk_bf16_f32 v97, v98, v99
	ds_write2_b64 v106, v[100:101], v[96:97] offset0:64 offset1:68
	v_pk_mul_f32 v[110:111], v[110:111], v[112:113] op_sel_hi:[1,0]
	v_pk_mul_f32 v[108:109], v[108:109], v[112:113] op_sel_hi:[1,0]
	s_waitcnt vmcnt(0)
	v_fmamk_f32 v96, v137, 0x3a800000, v129
	v_cvt_pk_bf16_f32 v108, v108, v109
	v_rsq_f32_e32 v96, v96
	v_cvt_pk_bf16_f32 v109, v110, v111
	ds_write2_b64 v106, v[108:109], v[104:105] offset0:32 offset1:36
	v_add_u32_e32 v97, 0x4200, v131
	v_pk_mul_f32 v[90:91], v[90:91], v[96:97] op_sel_hi:[1,0]
	v_pk_mul_f32 v[88:89], v[88:89], v[96:97] op_sel_hi:[1,0]
	v_pk_mul_f32 v[86:87], v[86:87], v[96:97] op_sel_hi:[1,0]
	v_pk_mul_f32 v[84:85], v[84:85], v[96:97] op_sel_hi:[1,0]
	v_pk_mul_f32 v[82:83], v[82:83], v[96:97] op_sel_hi:[1,0]
	v_pk_mul_f32 v[80:81], v[80:81], v[96:97] op_sel_hi:[1,0]
	v_cvt_pk_bf16_f32 v88, v88, v89
	v_cvt_pk_bf16_f32 v89, v90, v91
	v_add_u32_e32 v90, 0x4000, v131
	v_cvt_pk_bf16_f32 v84, v84, v85
	v_cvt_pk_bf16_f32 v85, v86, v87
	v_cvt_pk_bf16_f32 v80, v80, v81
	v_cvt_pk_bf16_f32 v81, v82, v83
	ds_write2_b64 v90, v[84:85], v[80:81] offset0:96 offset1:100
	v_pk_mul_f32 v[94:95], v[94:95], v[96:97] op_sel_hi:[1,0]
	v_pk_mul_f32 v[92:93], v[92:93], v[96:97] op_sel_hi:[1,0]
	s_waitcnt vmcnt(0)
	v_fmamk_f32 v80, v138, 0x3a800000, v129
	v_cvt_pk_bf16_f32 v92, v92, v93
	v_rsq_f32_e32 v80, v80
	v_cvt_pk_bf16_f32 v93, v94, v95
	ds_write2_b64 v90, v[92:93], v[88:89] offset0:64 offset1:68
	v_mov_b32_e32 v82, v80
	v_pk_mul_f32 v[74:75], v[74:75], v[82:83] op_sel_hi:[1,0]
	v_pk_mul_f32 v[72:73], v[72:73], v[82:83] op_sel_hi:[1,0]
	v_pk_mul_f32 v[70:71], v[70:71], v[82:83] op_sel_hi:[1,0]
	v_pk_mul_f32 v[68:69], v[68:69], v[82:83] op_sel_hi:[1,0]
	v_pk_mul_f32 v[66:67], v[66:67], v[82:83] op_sel_hi:[1,0]
	v_pk_mul_f32 v[64:65], v[64:65], v[82:83] op_sel_hi:[1,0]
	v_cvt_pk_bf16_f32 v72, v72, v73
	v_cvt_pk_bf16_f32 v73, v74, v75
	v_add_u32_e32 v74, 0x6000, v131
	v_cvt_pk_bf16_f32 v68, v68, v69
	v_cvt_pk_bf16_f32 v69, v70, v71
	v_cvt_pk_bf16_f32 v64, v64, v65
	v_cvt_pk_bf16_f32 v65, v66, v67
	ds_write2_b64 v74, v[68:69], v[64:65] offset0:128 offset1:132
	v_add_u32_e32 v80, 0x6300, v131
	v_pk_mul_f32 v[78:79], v[78:79], v[82:83] op_sel_hi:[1,0]
	v_pk_mul_f32 v[76:77], v[76:77], v[82:83] op_sel_hi:[1,0]
	v_add3_u32 v68, s12, v212, v189
	v_cvt_pk_bf16_f32 v76, v76, v77
	v_cvt_pk_bf16_f32 v77, v78, v79
	ds_write2_b64 v74, v[76:77], v[72:73] offset0:96 offset1:100
	v_add3_u32 v189, s12, v189, v212
	s_waitcnt vmcnt(0)
; __device__ __forceinline__ float row_rs(const float* ssq, int row) { return ssq ? rsqrtf(ssq[row] * (1.f / 1024.f) + RMS_EPS) : 1.f; }
; #define LAS __attribute__((address_space(3)))
; __device__ __forceinline__ unsigned pk2(float lo, float hi) { return pg8::cvt_pk_bf16(lo, hi); }
; __device__ __forceinline__ void stage_half(const bf16* g, LAS bf16* dst, int tid) {
;     v4u t[8];
; #pragma unroll
;     for (int i = 0; i < 8; ++i) { const int ch = tid + i * NT, r = ch >> 5, cc = ch & 31; t[i] = *(const v4u*)(g + (size_t)r * 1024 + cc * 8); }
; #pragma unroll
;     for (int i = 0; i < 8; ++i) { const int ch = tid + i * NT, r = ch >> 5, cc = ch & 31; *(LAS v4u*)(dst + r * XP + cc * 8) = t[i]; }
;     __device__ __forceinline__ void fused(f32x4 (&acc)[2][2][4][2], const pg8::Unit& u, int wr, int wc, int fr, int fq, LAS unsigned char* lds, int wid, int lane) const {
;         LAS bf16* QI = (LAS bf16*)lds;
; #pragma unroll
;         for (int ai = 0; ai < 2; ++ai)
; #pragma unroll
;             for (int m = 0; m < 4; ++m) { const int rl = ai * 128 + wr * 64 + m * 16 + fr; const float rs = pg8::row_rs(ssq, u.pm * 256 + rl);
; #pragma unroll
;                 for (int bj = 0; bj < 2; ++bj)
; #pragma unroll
;                     for (int n = 0; n < 2; ++n) { const f32x4 v = acc[ai][bj][m][n] * rs; v2u w; w.x = pk2(v[0], v[1]); w.y = pk2(v[2], v[3]);
;                         *(LAS v2u*)(QI + rl * XP + bj * 128 + wc * 32 + n * 16 + 4 * fq) = w; } }
	v_fmamk_f32 v64, v139, 0x3a800000, v129
	s_nop 0
	v_rsq_f32_e32 v64, v64
	s_nop 0
	v_mov_b32_e32 v66, v64
	v_pk_mul_f32 v[54:55], v[54:55], v[66:67] op_sel_hi:[1,0]
	v_pk_mul_f32 v[52:53], v[52:53], v[66:67] op_sel_hi:[1,0]
	v_pk_mul_f32 v[50:51], v[50:51], v[66:67] op_sel_hi:[1,0]
	v_pk_mul_f32 v[48:49], v[48:49], v[66:67] op_sel_hi:[1,0]
	v_cvt_pk_bf16_f32 v52, v52, v53
	v_cvt_pk_bf16_f32 v53, v54, v55
	v_cvt_pk_bf16_f32 v48, v48, v49
	v_cvt_pk_bf16_f32 v49, v50, v51
	v_add_u32_e32 v50, 0xe800, v113
	ds_write2_b64 v50, v[52:53], v[48:49] offset1:4
	v_pk_mul_f32 v[62:63], v[62:63], v[66:67] op_sel_hi:[1,0]
	v_pk_mul_f32 v[60:61], v[60:61], v[66:67] op_sel_hi:[1,0]
	v_pk_mul_f32 v[58:59], v[58:59], v[66:67] op_sel_hi:[1,0]
	v_pk_mul_f32 v[56:57], v[56:57], v[66:67] op_sel_hi:[1,0]
	v_cvt_pk_bf16_f32 v60, v60, v61
	v_cvt_pk_bf16_f32 v61, v62, v63
	v_cvt_pk_bf16_f32 v56, v56, v57
	v_cvt_pk_bf16_f32 v57, v58, v59
	v_add_u32_e32 v58, 0xe000, v113
	ds_write2_b64 v58, v[60:61], v[56:57] offset0:224 offset1:228
	v_add_u32_e32 v64, 0xe700, v113
	s_waitcnt vmcnt(0)
	v_fmamk_f32 v48, v140, 0x3a800000, v129
	s_nop 0
	v_rsq_f32_e32 v48, v48
	s_nop 0
	v_pk_mul_f32 v[38:39], v[38:39], v[48:49] op_sel_hi:[1,0]
	v_pk_mul_f32 v[36:37], v[36:37], v[48:49] op_sel_hi:[1,0]
	v_pk_mul_f32 v[34:35], v[34:35], v[48:49] op_sel_hi:[1,0]
	v_pk_mul_f32 v[32:33], v[32:33], v[48:49] op_sel_hi:[1,0]
	v_cvt_pk_bf16_f32 v36, v36, v37
	v_cvt_pk_bf16_f32 v37, v38, v39
	v_cvt_pk_bf16_f32 v32, v32, v33
	v_cvt_pk_bf16_f32 v33, v34, v35
	v_add_u32_e32 v34, 0xe800, v97
	ds_write2_b64 v34, v[36:37], v[32:33] offset1:4
	v_pk_mul_f32 v[46:47], v[46:47], v[48:49] op_sel_hi:[1,0]
	v_pk_mul_f32 v[44:45], v[44:45], v[48:49] op_sel_hi:[1,0]
	v_pk_mul_f32 v[42:43], v[42:43], v[48:49] op_sel_hi:[1,0]
	v_pk_mul_f32 v[40:41], v[40:41], v[48:49] op_sel_hi:[1,0]
	v_cvt_pk_bf16_f32 v44, v44, v45
	v_cvt_pk_bf16_f32 v45, v46, v47
	v_cvt_pk_bf16_f32 v40, v40, v41
	v_cvt_pk_bf16_f32 v41, v42, v43
	v_add_u32_e32 v42, 0xe000, v97
	ds_write2_b64 v42, v[44:45], v[40:41] offset0:224 offset1:228
	s_waitcnt vmcnt(0)
	v_fmamk_f32 v32, v141, 0x3a800000, v129
	s_nop 0
	v_rsq_f32_e32 v32, v32
	s_nop 0
	v_pk_mul_f32 v[22:23], v[22:23], v[32:33] op_sel_hi:[1,0]
	v_pk_mul_f32 v[20:21], v[20:21], v[32:33] op_sel_hi:[1,0]
	v_pk_mul_f32 v[18:19], v[18:19], v[32:33] op_sel_hi:[1,0]
	v_pk_mul_f32 v[16:17], v[16:17], v[32:33] op_sel_hi:[1,0]
	v_cvt_pk_bf16_f32 v20, v20, v21
	v_cvt_pk_bf16_f32 v21, v22, v23
	v_cvt_pk_bf16_f32 v16, v16, v17
	v_cvt_pk_bf16_f32 v17, v18, v19
	v_add_u32_e32 v18, 0xe800, v80
	ds_write2_b64 v18, v[20:21], v[16:17] offset1:4
	v_pk_mul_f32 v[30:31], v[30:31], v[32:33] op_sel_hi:[1,0]
	v_pk_mul_f32 v[28:29], v[28:29], v[32:33] op_sel_hi:[1,0]
	v_pk_mul_f32 v[26:27], v[26:27], v[32:33] op_sel_hi:[1,0]
	v_pk_mul_f32 v[24:25], v[24:25], v[32:33] op_sel_hi:[1,0]
	v_cvt_pk_bf16_f32 v28, v28, v29
	v_cvt_pk_bf16_f32 v29, v30, v31
	v_cvt_pk_bf16_f32 v24, v24, v25
	v_cvt_pk_bf16_f32 v25, v26, v27
	v_add_u32_e32 v26, 0xe000, v80
	v_or_b32_e32 v30, s30, v208
	ds_write2_b64 v26, v[28:29], v[24:25] offset0:224 offset1:228
	v_ashrrev_i32_e32 v34, 5, v30
	v_add_u32_e32 v20, 0xa00, v30
	v_add_u32_e32 v24, 0xc00, v30
	v_ashrrev_i32_e32 v44, 5, v20
	v_ashrrev_i32_e32 v46, 5, v24
	v_ashrrev_i32_e32 v35, 31, v34
	v_ashrrev_i32_e32 v45, 31, v44
	v_ashrrev_i32_e32 v47, 31, v46
	v_lshlrev_b64 v[192:193], 11, v[34:35]
	v_lshlrev_b64 v[202:203], 11, v[44:45]
	v_lshlrev_b64 v[204:205], 11, v[46:47]
	v_mul_lo_u32 v34, v34, s14
	v_add_u32_e32 v223, v216, v34
	v_add_u32_e32 v230, v215, v34
	s_waitcnt vmcnt(0)
	v_fmac_f32_e32 v129, 0x3a800000, v142
	s_lshl_b32 s6, s15, 8
	v_rsq_f32_e32 v16, v129
	s_ashr_i32 s7, s6, 31
	s_lshl_b64 s[4:5], s[6:7], 11
	s_add_u32 s10, s48, s4
	s_addc_u32 s19, s49, s5
	s_lshl_b32 s16, s34, 8
	v_pk_mul_f32 v[14:15], v[14:15], v[16:17] op_sel_hi:[1,0]
	v_pk_mul_f32 v[12:13], v[12:13], v[16:17] op_sel_hi:[1,0]
	v_pk_mul_f32 v[10:11], v[10:11], v[16:17] op_sel_hi:[1,0]
	v_pk_mul_f32 v[8:9], v[8:9], v[16:17] op_sel_hi:[1,0]
	v_pk_mul_f32 v[6:7], v[6:7], v[16:17] op_sel_hi:[1,0]
	v_pk_mul_f32 v[4:5], v[4:5], v[16:17] op_sel_hi:[1,0]
	v_pk_mul_f32 v[2:3], v[2:3], v[16:17] op_sel_hi:[1,0]
	v_pk_mul_f32 v[0:1], v[0:1], v[16:17] op_sel_hi:[1,0]
	s_ashr_i32 s17, s16, 31
	v_cvt_pk_bf16_f32 v12, v12, v13
	v_cvt_pk_bf16_f32 v13, v14, v15
	v_cvt_pk_bf16_f32 v8, v8, v9
	v_cvt_pk_bf16_f32 v9, v10, v11
	v_add_u32_e32 v10, 0x6000, v64
	v_cvt_pk_bf16_f32 v4, v4, v5
	v_cvt_pk_bf16_f32 v5, v6, v7
	v_cvt_pk_bf16_f32 v0, v0, v1
	v_cvt_pk_bf16_f32 v1, v2, v3
	s_lshl_b64 s[4:5], s[16:17], 1
	ds_write2_b64 v10, v[12:13], v[8:9] offset0:96 offset1:100
	ds_write2_b64 v10, v[4:5], v[0:1] offset0:128 offset1:132
	s_add_u32 s18, s10, s4
	v_add_u32_e32 v4, 0x200, v30
	v_add_u32_e32 v8, 0x400, v30
	v_add_u32_e32 v12, 0x600, v30
	v_add_u32_e32 v16, 0x800, v30
	v_add_u32_e32 v30, 0xe00, v30
	s_addc_u32 s19, s19, s5
	v_ashrrev_i32_e32 v36, 5, v4
	v_ashrrev_i32_e32 v38, 5, v8
	v_ashrrev_i32_e32 v40, 5, v12
	v_ashrrev_i32_e32 v42, 5, v16
	v_ashrrev_i32_e32 v48, 5, v30
	v_mul_lo_u32 v0, v214, s14
	v_lshl_add_u64 v[32:33], s[18:19], 0, v[190:191]
	s_mov_b64 s[18:19], 0x5600000
	v_ashrrev_i32_e32 v37, 31, v36
	v_ashrrev_i32_e32 v39, 31, v38
	v_ashrrev_i32_e32 v41, 31, v40
	v_ashrrev_i32_e32 v43, 31, v42
	v_ashrrev_i32_e32 v49, 31, v48
	v_add3_u32 v0, 0, v130, v0
	v_lshl_add_u64 v[28:29], v[32:33], 0, s[18:19]
	v_lshlrev_b64 v[194:195], 11, v[36:37]
	v_lshlrev_b64 v[196:197], 11, v[38:39]
	v_lshlrev_b64 v[198:199], 11, v[40:41]
	v_lshlrev_b64 v[200:201], 11, v[42:43]
	v_lshlrev_b64 v[206:207], 11, v[48:49]
	s_waitcnt lgkmcnt(0)
	s_barrier
; #define LAS __attribute__((address_space(3)))
; __device__ __forceinline__ void stage_half(const bf16* g, LAS bf16* dst, int tid) {
;     v4u t[8];
; #pragma unroll
;     for (int i = 0; i < 8; ++i) { const int ch = tid + i * NT, r = ch >> 5, cc = ch & 31; t[i] = *(const v4u*)(g + (size_t)r * 1024 + cc * 8); }
; #pragma unroll
;     for (int i = 0; i < 8; ++i) { const int ch = tid + i * NT, r = ch >> 5, cc = ch & 31; *(LAS v4u*)(dst + r * XP + cc * 8) = t[i]; }
; }
; __device__ __forceinline__ void xattn_core(unsigned char* ws, LAS unsigned char* lds, int b, int hd, int qb, int tid, const bf16x8 (&qf)[16]) {
;     const int lane = tid & 63, wave = tid >> 6, r32 = lane & 31, hh = lane >> 5;
;     LAS bf16* L0 = (LAS bf16*)lds; LAS bf16* L1 = L0 + 128 * XP;
;     const bf16* Kg = (const bf16*)(ws + WS_KB) + (size_t)(b * 256) * 1024 + hd * 256;
;     const bf16* Vg = (const bf16*)(ws + WS_VT) + (size_t)(hd * 256) * 1024 + b * 256;
;     stage_half(Kg, L0, tid); stage_half(Kg + (size_t)128 * 1024, L1, tid);
;     const int q0 = b * SEQ + qb * 256 + 32 * wave;
;     __syncthreads();
;     f32x16 sacc[8];
; #pragma unroll
;     for (int mt = 0; mt < 8; ++mt) {
; #pragma unroll
;         for (int r = 0; r < 16; ++r) sacc[mt][r] = 0.f;
;         const LAS bf16* kp = (mt < 4 ? L0 : L1) + ((mt & 3) * 32 + r32) * XP + 8 * hh;
; #pragma unroll
;         for (int ds = 0; ds < 16; ++ds) { const bf16x8 kf = *(const LAS bf16x8*)(kp + 16 * ds); sacc[mt] = __builtin_amdgcn_mfma_f32_32x32x16_bf16(kf, qf[ds], sacc[mt], 0, 0, 0); } }
;     __device__ __forceinline__ void fused(f32x4 (&acc)[2][2][4][2], const pg8::Unit& u, int wr, int wc, int fr, int fq, LAS unsigned char* lds, int wid, int lane) const {
;     ...
;         const int r32 = lane & 31, hh = lane >> 5; bf16x8 qf[16];
; #pragma unroll
;         for (int ds = 0; ds < 16; ++ds) qf[ds] = *(const LAS bf16x8*)(QI + (32 * wid + r32) * XP + 16 * ds + 8 * hh);
;         __syncthreads();
	ds_read_b128 v[112:115], v0
	ds_read_b128 v[184:187], v0 offset:32
	ds_read_b128 v[180:183], v0 offset:64
	ds_read_b128 v[176:179], v0 offset:96
	ds_read_b128 v[172:175], v0 offset:128
	ds_read_b128 v[168:171], v0 offset:160
	ds_read_b128 v[164:167], v0 offset:192
	ds_read_b128 v[160:163], v0 offset:224
	ds_read_b128 v[156:159], v0 offset:256
	ds_read_b128 v[152:155], v0 offset:288
	ds_read_b128 v[148:151], v0 offset:320
	ds_read_b128 v[144:147], v0 offset:352
	ds_read_b128 v[140:143], v0 offset:384
	ds_read_b128 v[136:139], v0 offset:416
	ds_read_b128 v[132:135], v0 offset:448
	ds_read_b128 v[128:131], v0 offset:480
	v_lshl_add_u64 v[0:1], v[28:29], 0, v[192:193]
	v_lshl_add_u64 v[4:5], v[28:29], 0, v[194:195]
	v_lshl_add_u64 v[8:9], v[28:29], 0, v[196:197]
	v_lshl_add_u64 v[12:13], v[28:29], 0, v[198:199]
	v_lshl_add_u64 v[16:17], v[28:29], 0, v[200:201]
	v_lshl_add_u64 v[20:21], v[28:29], 0, v[202:203]
	v_lshl_add_u64 v[24:25], v[28:29], 0, v[204:205]
	v_lshl_add_u64 v[28:29], v[28:29], 0, v[206:207]
	s_waitcnt lgkmcnt(0)
	s_barrier
	s_mov_b64 s[18:19], 0x5640000
	v_lshl_add_u64 v[100:101], v[32:33], 0, s[18:19]
	v_lshl_add_u64 v[72:73], v[100:101], 0, v[192:193]
	v_lshl_add_u64 v[76:77], v[100:101], 0, v[194:195]
	v_lshl_add_u64 v[80:81], v[100:101], 0, v[196:197]
	v_lshl_add_u64 v[84:85], v[100:101], 0, v[198:199]
	v_lshl_add_u64 v[88:89], v[100:101], 0, v[200:201]
	v_lshl_add_u64 v[92:93], v[100:101], 0, v[202:203]
	v_lshl_add_u64 v[96:97], v[100:101], 0, v[204:205]
	v_lshl_add_u64 v[100:101], v[100:101], 0, v[206:207]
	global_load_dwordx4 v[0:3], v[0:1], off
	v_mul_lo_u32 v35, v36, s14
	global_load_dwordx4 v[4:7], v[4:5], off
	v_mul_lo_u32 v36, v38, s14
	global_load_dwordx4 v[8:11], v[8:9], off
	v_mul_lo_u32 v37, v40, s14
	global_load_dwordx4 v[12:15], v[12:13], off
	v_mul_lo_u32 v38, v42, s14
	global_load_dwordx4 v[16:19], v[16:17], off
	v_mul_lo_u32 v39, v44, s14
	global_load_dwordx4 v[20:23], v[20:21], off
	v_mul_lo_u32 v40, v46, s14
	global_load_dwordx4 v[24:27], v[24:25], off
	v_mul_lo_u32 v41, v48, s14
	global_load_dwordx4 v[28:31], v[28:29], off
	global_load_dwordx4 v[72:75], v[72:73], off
	global_load_dwordx4 v[76:79], v[76:77], off
	global_load_dwordx4 v[80:83], v[80:81], off
	global_load_dwordx4 v[84:87], v[84:85], off
	global_load_dwordx4 v[88:91], v[88:89], off
	global_load_dwordx4 v[92:95], v[92:93], off
	global_load_dwordx4 v[96:99], v[96:97], off
	global_load_dwordx4 v[100:103], v[100:101], off
	v_add_u32_e32 v222, v216, v35
	v_add_u32_e32 v221, v216, v36
	v_add_u32_e32 v220, v216, v37
	v_add_u32_e32 v219, v216, v38
	v_add_u32_e32 v218, v216, v39
	v_add_u32_e32 v217, v216, v40
	v_add_u32_e32 v216, v216, v41
	s_mov_b64 s[18:19], 0x5640000
	v_add_u32_e32 v224, v215, v35
	v_add_u32_e32 v225, v215, v36
	v_add_u32_e32 v226, v215, v37
	v_add_u32_e32 v227, v215, v38
	v_add_u32_e32 v228, v215, v39
	v_add_u32_e32 v229, v215, v40
	v_add_u32_e32 v215, v215, v41
	s_lshl_b64 s[16:17], s[16:17], 11
	s_add_u32 s16, s48, s16
	s_addc_u32 s17, s49, s17
	s_and_b32 s10, s13, 0xf00
	s_lshl_b64 s[6:7], s[6:7], 1
	s_add_u32 s16, s16, s6
	s_addc_u32 s17, s17, s7
	s_lshl_b32 s6, s15, 12
	s_mov_b64 s[14:15], 0x5800000
	s_mov_b32 s7, 0xff61b1e6
	s_or_b32 s6, s10, s6
	s_waitcnt vmcnt(15)
	ds_write_b128 v223, v[0:3]
	s_waitcnt vmcnt(14)
	ds_write_b128 v222, v[4:7]
	s_waitcnt vmcnt(13)
	ds_write_b128 v221, v[8:11]
	s_waitcnt vmcnt(12)
	ds_write_b128 v220, v[12:15]
	s_waitcnt vmcnt(11)
	ds_write_b128 v219, v[16:19]
	s_waitcnt vmcnt(10)
	ds_write_b128 v218, v[20:23]
	s_waitcnt vmcnt(9)
	ds_write_b128 v217, v[24:27]
	s_waitcnt vmcnt(8)
	ds_write_b128 v216, v[28:31]
	s_waitcnt vmcnt(7)
	ds_write_b128 v230, v[72:75]
	s_waitcnt vmcnt(6)
	ds_write_b128 v224, v[76:79]
	s_waitcnt vmcnt(5)
	ds_write_b128 v225, v[80:83]
	s_waitcnt vmcnt(4)
	ds_write_b128 v226, v[84:87]
	s_waitcnt vmcnt(3)
	ds_write_b128 v227, v[88:91]
	s_waitcnt vmcnt(2)
	ds_write_b128 v228, v[92:95]
	s_waitcnt vmcnt(1)
	ds_write_b128 v229, v[96:99]
	s_waitcnt vmcnt(0)
	ds_write_b128 v215, v[100:103]
	s_waitcnt lgkmcnt(0)
	s_barrier
	ds_read_b128 v[236:239], v213
	ds_read_b128 v[240:243], v213 offset:32
	ds_read_b128 v[244:247], v213 offset:64
	s_waitcnt lgkmcnt(2)
	v_mfma_f32_32x32x16_bf16 v[96:111], v[236:239], v[112:115], 0
	ds_read_b128 v[236:239], v213 offset:96
	s_waitcnt lgkmcnt(2)
	v_mfma_f32_32x32x16_bf16 v[96:111], v[240:243], v[184:187], v[96:111]
	ds_read_b128 v[240:243], v213 offset:128
	s_waitcnt lgkmcnt(2)
	v_mfma_f32_32x32x16_bf16 v[96:111], v[244:247], v[180:183], v[96:111]
	ds_read_b128 v[244:247], v213 offset:160
	s_waitcnt lgkmcnt(2)
	v_mfma_f32_32x32x16_bf16 v[96:111], v[236:239], v[176:179], v[96:111]
	ds_read_b128 v[236:239], v213 offset:192
	s_waitcnt lgkmcnt(2)
	v_mfma_f32_32x32x16_bf16 v[96:111], v[240:243], v[172:175], v[96:111]
	ds_read_b128 v[240:243], v213 offset:224
	s_waitcnt lgkmcnt(2)
	v_mfma_f32_32x32x16_bf16 v[96:111], v[244:247], v[168:171], v[96:111]
	ds_read_b128 v[244:247], v213 offset:256
	s_waitcnt lgkmcnt(2)
	v_mfma_f32_32x32x16_bf16 v[96:111], v[236:239], v[164:167], v[96:111]
	ds_read_b128 v[236:239], v213 offset:288
	s_waitcnt lgkmcnt(2)
	v_mfma_f32_32x32x16_bf16 v[96:111], v[240:243], v[160:163], v[96:111]
	ds_read_b128 v[240:243], v213 offset:320
	s_waitcnt lgkmcnt(2)
	v_mfma_f32_32x32x16_bf16 v[96:111], v[244:247], v[156:159], v[96:111]
	ds_read_b128 v[244:247], v213 offset:352
	s_waitcnt lgkmcnt(2)
	v_mfma_f32_32x32x16_bf16 v[96:111], v[236:239], v[152:155], v[96:111]
	ds_read_b128 v[236:239], v213 offset:384
	s_waitcnt lgkmcnt(2)
	v_mfma_f32_32x32x16_bf16 v[96:111], v[240:243], v[148:151], v[96:111]
	ds_read_b128 v[240:243], v213 offset:416
	s_waitcnt lgkmcnt(2)
; #define LAS __attribute__((address_space(3)))
; __device__ __forceinline__ void xattn_core(unsigned char* ws, LAS unsigned char* lds, int b, int hd, int qb, int tid, const bf16x8 (&qf)[16]) {
;     ...
;     for (int mt = 0; mt < 8; ++mt) {
; #pragma unroll
;         for (int r = 0; r < 16; ++r) sacc[mt][r] = 0.f;
;         const LAS bf16* kp = (mt < 4 ? L0 : L1) + ((mt & 3) * 32 + r32) * XP + 8 * hh;
; #pragma unroll
;         for (int ds = 0; ds < 16; ++ds) { const bf16x8 kf = *(const LAS bf16x8*)(kp + 16 * ds); sacc[mt] = __builtin_amdgcn_mfma_f32_32x32x16_bf16(kf, qf[ds], sacc[mt], 0, 0, 0); } }
	v_mfma_f32_32x32x16_bf16 v[96:111], v[244:247], v[144:147], v[96:111]
	ds_read_b128 v[244:247], v213 offset:448
	s_waitcnt lgkmcnt(2)
	v_mfma_f32_32x32x16_bf16 v[96:111], v[236:239], v[140:143], v[96:111]
	ds_read_b128 v[236:239], v213 offset:480
	s_waitcnt lgkmcnt(2)
	v_mfma_f32_32x32x16_bf16 v[96:111], v[240:243], v[136:139], v[96:111]
	ds_read_b128 v[240:243], v213 offset:16896
	s_waitcnt lgkmcnt(2)
	v_mfma_f32_32x32x16_bf16 v[96:111], v[244:247], v[132:135], v[96:111]
	ds_read_b128 v[244:247], v213 offset:16928
	s_waitcnt lgkmcnt(2)
	v_mfma_f32_32x32x16_bf16 v[96:111], v[236:239], v[128:131], v[96:111]
	ds_read_b128 v[236:239], v213 offset:16960
	s_waitcnt lgkmcnt(2)
	v_mfma_f32_32x32x16_bf16 v[32:47], v[240:243], v[112:115], 0
	ds_read_b128 v[240:243], v213 offset:16992
	s_waitcnt lgkmcnt(2)
	v_mfma_f32_32x32x16_bf16 v[32:47], v[244:247], v[184:187], v[32:47]
	ds_read_b128 v[244:247], v213 offset:17024
	s_waitcnt lgkmcnt(2)
	v_mfma_f32_32x32x16_bf16 v[32:47], v[236:239], v[180:183], v[32:47]
	ds_read_b128 v[236:239], v213 offset:17056
	s_waitcnt lgkmcnt(2)
	v_mfma_f32_32x32x16_bf16 v[32:47], v[240:243], v[176:179], v[32:47]
	ds_read_b128 v[240:243], v213 offset:17088
	s_waitcnt lgkmcnt(2)
	v_mfma_f32_32x32x16_bf16 v[32:47], v[244:247], v[172:175], v[32:47]
	ds_read_b128 v[244:247], v213 offset:17120
	s_waitcnt lgkmcnt(2)
	v_mfma_f32_32x32x16_bf16 v[32:47], v[236:239], v[168:171], v[32:47]
	ds_read_b128 v[236:239], v213 offset:17152
	s_waitcnt lgkmcnt(2)
	v_mfma_f32_32x32x16_bf16 v[32:47], v[240:243], v[164:167], v[32:47]
	ds_read_b128 v[240:243], v213 offset:17184
	s_waitcnt lgkmcnt(2)
	v_mfma_f32_32x32x16_bf16 v[32:47], v[244:247], v[160:163], v[32:47]
	ds_read_b128 v[244:247], v213 offset:17216
	s_waitcnt lgkmcnt(2)
	v_mfma_f32_32x32x16_bf16 v[32:47], v[236:239], v[156:159], v[32:47]
	ds_read_b128 v[236:239], v213 offset:17248
	s_waitcnt lgkmcnt(2)
	v_mfma_f32_32x32x16_bf16 v[32:47], v[240:243], v[152:155], v[32:47]
	ds_read_b128 v[240:243], v213 offset:17280
	s_waitcnt lgkmcnt(2)
	v_mfma_f32_32x32x16_bf16 v[32:47], v[244:247], v[148:151], v[32:47]
	ds_read_b128 v[244:247], v213 offset:17312
	s_waitcnt lgkmcnt(2)
	v_mfma_f32_32x32x16_bf16 v[32:47], v[236:239], v[144:147], v[32:47]
	ds_read_b128 v[236:239], v213 offset:17344
	s_waitcnt lgkmcnt(2)
	v_mfma_f32_32x32x16_bf16 v[32:47], v[240:243], v[140:143], v[32:47]
	ds_read_b128 v[240:243], v213 offset:17376
	s_waitcnt lgkmcnt(2)
	v_mfma_f32_32x32x16_bf16 v[32:47], v[244:247], v[136:139], v[32:47]
	ds_read_b128 v[244:247], v213 offset:33792
	s_waitcnt lgkmcnt(2)
	v_mfma_f32_32x32x16_bf16 v[32:47], v[236:239], v[132:135], v[32:47]
	ds_read_b128 v[236:239], v213 offset:33824
	s_waitcnt lgkmcnt(2)
	v_mfma_f32_32x32x16_bf16 v[32:47], v[240:243], v[128:131], v[32:47]
	ds_read_b128 v[240:243], v213 offset:33856
	s_waitcnt lgkmcnt(2)
	v_mfma_f32_32x32x16_bf16 v[16:31], v[244:247], v[112:115], 0
	ds_read_b128 v[244:247], v213 offset:33888
	s_waitcnt lgkmcnt(2)
	v_mfma_f32_32x32x16_bf16 v[16:31], v[236:239], v[184:187], v[16:31]
	ds_read_b128 v[236:239], v213 offset:33920
	s_waitcnt lgkmcnt(2)
	v_mfma_f32_32x32x16_bf16 v[16:31], v[240:243], v[180:183], v[16:31]
	ds_read_b128 v[240:243], v213 offset:33952
	s_waitcnt lgkmcnt(2)
	v_mfma_f32_32x32x16_bf16 v[16:31], v[244:247], v[176:179], v[16:31]
	ds_read_b128 v[244:247], v213 offset:33984
	s_waitcnt lgkmcnt(2)
	v_mfma_f32_32x32x16_bf16 v[16:31], v[236:239], v[172:175], v[16:31]
	ds_read_b128 v[236:239], v213 offset:34016
	s_waitcnt lgkmcnt(2)
	v_mfma_f32_32x32x16_bf16 v[16:31], v[240:243], v[168:171], v[16:31]
	ds_read_b128 v[240:243], v213 offset:34048
	s_waitcnt lgkmcnt(2)
	v_mfma_f32_32x32x16_bf16 v[16:31], v[244:247], v[164:167], v[16:31]
	ds_read_b128 v[244:247], v213 offset:34080
	s_waitcnt lgkmcnt(2)
	v_mfma_f32_32x32x16_bf16 v[16:31], v[236:239], v[160:163], v[16:31]
	ds_read_b128 v[236:239], v213 offset:34112
	s_waitcnt lgkmcnt(2)
	v_mfma_f32_32x32x16_bf16 v[16:31], v[240:243], v[156:159], v[16:31]
	ds_read_b128 v[240:243], v213 offset:34144
	s_waitcnt lgkmcnt(2)
	v_mfma_f32_32x32x16_bf16 v[16:31], v[244:247], v[152:155], v[16:31]
	ds_read_b128 v[244:247], v213 offset:34176
	s_waitcnt lgkmcnt(2)
	v_mfma_f32_32x32x16_bf16 v[16:31], v[236:239], v[148:151], v[16:31]
	ds_read_b128 v[236:239], v213 offset:34208
	s_waitcnt lgkmcnt(2)
	v_mfma_f32_32x32x16_bf16 v[16:31], v[240:243], v[144:147], v[16:31]
	ds_read_b128 v[240:243], v213 offset:34240
	s_waitcnt lgkmcnt(2)
	v_mfma_f32_32x32x16_bf16 v[16:31], v[244:247], v[140:143], v[16:31]
	ds_read_b128 v[244:247], v213 offset:34272
	s_waitcnt lgkmcnt(2)
	v_mfma_f32_32x32x16_bf16 v[16:31], v[236:239], v[136:139], v[16:31]
	ds_read_b128 v[236:239], v213 offset:50688
	s_waitcnt lgkmcnt(2)
	v_mfma_f32_32x32x16_bf16 v[16:31], v[240:243], v[132:135], v[16:31]
	ds_read_b128 v[240:243], v213 offset:50720
	s_waitcnt lgkmcnt(2)
	v_mfma_f32_32x32x16_bf16 v[16:31], v[244:247], v[128:131], v[16:31]
	ds_read_b128 v[244:247], v213 offset:50752
	s_waitcnt lgkmcnt(2)
	v_mfma_f32_32x32x16_bf16 v[0:15], v[236:239], v[112:115], 0
	ds_read_b128 v[236:239], v213 offset:50784
	s_waitcnt lgkmcnt(2)
	v_mfma_f32_32x32x16_bf16 v[0:15], v[240:243], v[184:187], v[0:15]
	ds_read_b128 v[240:243], v213 offset:50816
	s_waitcnt lgkmcnt(2)
	v_mfma_f32_32x32x16_bf16 v[0:15], v[244:247], v[180:183], v[0:15]
	ds_read_b128 v[244:247], v213 offset:50848
	s_waitcnt lgkmcnt(2)
	v_mfma_f32_32x32x16_bf16 v[0:15], v[236:239], v[176:179], v[0:15]
	ds_read_b128 v[236:239], v213 offset:50880
	s_waitcnt lgkmcnt(2)
	v_mfma_f32_32x32x16_bf16 v[0:15], v[240:243], v[172:175], v[0:15]
	ds_read_b128 v[240:243], v213 offset:50912
	s_waitcnt lgkmcnt(2)
; #define LAS __attribute__((address_space(3)))
; __device__ __forceinline__ void xattn_core(unsigned char* ws, LAS unsigned char* lds, int b, int hd, int qb, int tid, const bf16x8 (&qf)[16]) {
;     ...
;     for (int mt = 0; mt < 8; ++mt) {
; #pragma unroll
;         for (int r = 0; r < 16; ++r) sacc[mt][r] = 0.f;
;         const LAS bf16* kp = (mt < 4 ? L0 : L1) + ((mt & 3) * 32 + r32) * XP + 8 * hh;
; #pragma unroll
;         for (int ds = 0; ds < 16; ++ds) { const bf16x8 kf = *(const LAS bf16x8*)(kp + 16 * ds); sacc[mt] = __builtin_amdgcn_mfma_f32_32x32x16_bf16(kf, qf[ds], sacc[mt], 0, 0, 0); } }
	v_mfma_f32_32x32x16_bf16 v[0:15], v[244:247], v[168:171], v[0:15]
	ds_read_b128 v[244:247], v213 offset:50944
	s_waitcnt lgkmcnt(2)
	v_mfma_f32_32x32x16_bf16 v[0:15], v[236:239], v[164:167], v[0:15]
	ds_read_b128 v[236:239], v213 offset:50976
	s_waitcnt lgkmcnt(2)
	v_mfma_f32_32x32x16_bf16 v[0:15], v[240:243], v[160:163], v[0:15]
	ds_read_b128 v[240:243], v213 offset:51008
	s_waitcnt lgkmcnt(2)
	v_mfma_f32_32x32x16_bf16 v[0:15], v[244:247], v[156:159], v[0:15]
	ds_read_b128 v[244:247], v213 offset:51040
	s_waitcnt lgkmcnt(2)
	v_mfma_f32_32x32x16_bf16 v[0:15], v[236:239], v[152:155], v[0:15]
	ds_read_b128 v[236:239], v213 offset:51072
	s_waitcnt lgkmcnt(2)
	v_mfma_f32_32x32x16_bf16 v[0:15], v[240:243], v[148:151], v[0:15]
	ds_read_b128 v[240:243], v213 offset:51104
	s_waitcnt lgkmcnt(2)
	v_mfma_f32_32x32x16_bf16 v[0:15], v[244:247], v[144:147], v[0:15]
	ds_read_b128 v[244:247], v213 offset:51136
	s_waitcnt lgkmcnt(2)
	v_mfma_f32_32x32x16_bf16 v[0:15], v[236:239], v[140:143], v[0:15]
	ds_read_b128 v[236:239], v213 offset:51168
	s_waitcnt lgkmcnt(2)
	v_mfma_f32_32x32x16_bf16 v[0:15], v[240:243], v[136:139], v[0:15]
	ds_read_b128 v[240:243], v68
	s_waitcnt lgkmcnt(2)
	v_mfma_f32_32x32x16_bf16 v[0:15], v[244:247], v[132:135], v[0:15]
	ds_read_b128 v[244:247], v68 offset:32
	s_waitcnt lgkmcnt(2)
	v_mfma_f32_32x32x16_bf16 v[0:15], v[236:239], v[128:131], v[0:15]
	ds_read_b128 v[236:239], v68 offset:64
	s_waitcnt lgkmcnt(2)
	v_mfma_f32_32x32x16_bf16 v[48:63], v[240:243], v[112:115], 0
	ds_read_b128 v[240:243], v68 offset:96
	s_waitcnt lgkmcnt(2)
	v_mfma_f32_32x32x16_bf16 v[48:63], v[244:247], v[184:187], v[48:63]
	ds_read_b128 v[244:247], v68 offset:128
	s_waitcnt lgkmcnt(2)
	v_mfma_f32_32x32x16_bf16 v[48:63], v[236:239], v[180:183], v[48:63]
	ds_read_b128 v[236:239], v68 offset:160
	s_waitcnt lgkmcnt(2)
	v_mfma_f32_32x32x16_bf16 v[48:63], v[240:243], v[176:179], v[48:63]
	ds_read_b128 v[240:243], v68 offset:192
	s_waitcnt lgkmcnt(2)
	v_mfma_f32_32x32x16_bf16 v[48:63], v[244:247], v[172:175], v[48:63]
	ds_read_b128 v[244:247], v68 offset:224
	s_waitcnt lgkmcnt(2)
	v_mfma_f32_32x32x16_bf16 v[48:63], v[236:239], v[168:171], v[48:63]
	ds_read_b128 v[236:239], v68 offset:256
	s_waitcnt lgkmcnt(2)
	v_mfma_f32_32x32x16_bf16 v[48:63], v[240:243], v[164:167], v[48:63]
	ds_read_b128 v[240:243], v68 offset:288
	s_waitcnt lgkmcnt(2)
	v_mfma_f32_32x32x16_bf16 v[48:63], v[244:247], v[160:163], v[48:63]
	ds_read_b128 v[244:247], v68 offset:320
	s_waitcnt lgkmcnt(2)
	v_mfma_f32_32x32x16_bf16 v[48:63], v[236:239], v[156:159], v[48:63]
	ds_read_b128 v[236:239], v68 offset:352
	s_waitcnt lgkmcnt(2)
	v_mfma_f32_32x32x16_bf16 v[48:63], v[240:243], v[152:155], v[48:63]
	ds_read_b128 v[240:243], v68 offset:384
	s_waitcnt lgkmcnt(2)
	v_mfma_f32_32x32x16_bf16 v[48:63], v[244:247], v[148:151], v[48:63]
	ds_read_b128 v[244:247], v68 offset:416
	s_waitcnt lgkmcnt(2)
	v_mfma_f32_32x32x16_bf16 v[48:63], v[236:239], v[144:147], v[48:63]
	ds_read_b128 v[236:239], v68 offset:448
	s_waitcnt lgkmcnt(2)
	v_mfma_f32_32x32x16_bf16 v[48:63], v[240:243], v[140:143], v[48:63]
	ds_read_b128 v[240:243], v68 offset:480
	s_waitcnt lgkmcnt(2)
	v_mfma_f32_32x32x16_bf16 v[48:63], v[244:247], v[136:139], v[48:63]
	ds_read_b128 v[244:247], v189 offset:16896
	s_waitcnt lgkmcnt(2)
	v_mfma_f32_32x32x16_bf16 v[48:63], v[236:239], v[132:135], v[48:63]
	ds_read_b128 v[236:239], v189 offset:16928
	s_waitcnt lgkmcnt(2)
	v_mfma_f32_32x32x16_bf16 v[48:63], v[240:243], v[128:131], v[48:63]
	ds_read_b128 v[240:243], v189 offset:16960
	s_waitcnt lgkmcnt(2)
	v_mfma_f32_32x32x16_bf16 v[80:95], v[244:247], v[112:115], 0
	ds_read_b128 v[244:247], v189 offset:16992
	s_waitcnt lgkmcnt(2)
	v_mfma_f32_32x32x16_bf16 v[80:95], v[236:239], v[184:187], v[80:95]
	ds_read_b128 v[236:239], v189 offset:17024
	s_waitcnt lgkmcnt(2)
	v_mfma_f32_32x32x16_bf16 v[80:95], v[240:243], v[180:183], v[80:95]
	ds_read_b128 v[240:243], v189 offset:17056
	s_waitcnt lgkmcnt(2)
	v_mfma_f32_32x32x16_bf16 v[80:95], v[244:247], v[176:179], v[80:95]
	ds_read_b128 v[244:247], v189 offset:17088
	s_waitcnt lgkmcnt(2)
	v_mfma_f32_32x32x16_bf16 v[80:95], v[236:239], v[172:175], v[80:95]
	ds_read_b128 v[236:239], v189 offset:17120
	s_waitcnt lgkmcnt(2)
	v_mfma_f32_32x32x16_bf16 v[80:95], v[240:243], v[168:171], v[80:95]
	ds_read_b128 v[240:243], v189 offset:17152
	s_waitcnt lgkmcnt(2)
	v_mfma_f32_32x32x16_bf16 v[80:95], v[244:247], v[164:167], v[80:95]
	ds_read_b128 v[244:247], v189 offset:17184
	s_waitcnt lgkmcnt(2)
	v_mfma_f32_32x32x16_bf16 v[80:95], v[236:239], v[160:163], v[80:95]
	ds_read_b128 v[236:239], v189 offset:17216
	s_waitcnt lgkmcnt(2)
	v_mfma_f32_32x32x16_bf16 v[80:95], v[240:243], v[156:159], v[80:95]
	ds_read_b128 v[240:243], v189 offset:17248
	s_waitcnt lgkmcnt(2)
	v_mfma_f32_32x32x16_bf16 v[80:95], v[244:247], v[152:155], v[80:95]
	ds_read_b128 v[244:247], v189 offset:17280
	s_waitcnt lgkmcnt(2)
	v_mfma_f32_32x32x16_bf16 v[80:95], v[236:239], v[148:151], v[80:95]
	ds_read_b128 v[236:239], v189 offset:17312
	s_waitcnt lgkmcnt(2)
	v_mfma_f32_32x32x16_bf16 v[80:95], v[240:243], v[144:147], v[80:95]
	ds_read_b128 v[240:243], v189 offset:17344
	s_waitcnt lgkmcnt(2)
	v_mfma_f32_32x32x16_bf16 v[80:95], v[244:247], v[140:143], v[80:95]
	ds_read_b128 v[244:247], v189 offset:17376
	s_waitcnt lgkmcnt(2)
	v_mfma_f32_32x32x16_bf16 v[80:95], v[236:239], v[136:139], v[80:95]
	ds_read_b128 v[236:239], v189 offset:33792
	s_waitcnt lgkmcnt(2)
	v_mfma_f32_32x32x16_bf16 v[80:95], v[240:243], v[132:135], v[80:95]
	ds_read_b128 v[240:243], v189 offset:33824
	s_waitcnt lgkmcnt(2)
	v_mfma_f32_32x32x16_bf16 v[80:95], v[244:247], v[128:131], v[80:95]
	ds_read_b128 v[244:247], v189 offset:33856
	s_waitcnt lgkmcnt(2)
; #define LAS __attribute__((address_space(3)))
; __device__ __forceinline__ void xattn_core(unsigned char* ws, LAS unsigned char* lds, int b, int hd, int qb, int tid, const bf16x8 (&qf)[16]) {
;     ...
;     for (int mt = 0; mt < 8; ++mt) {
; #pragma unroll
;         for (int r = 0; r < 16; ++r) sacc[mt][r] = 0.f;
;         const LAS bf16* kp = (mt < 4 ? L0 : L1) + ((mt & 3) * 32 + r32) * XP + 8 * hh;
; #pragma unroll
;         for (int ds = 0; ds < 16; ++ds) { const bf16x8 kf = *(const LAS bf16x8*)(kp + 16 * ds); sacc[mt] = __builtin_amdgcn_mfma_f32_32x32x16_bf16(kf, qf[ds], sacc[mt], 0, 0, 0); } }
;     __syncthreads();
;     stage_half(Vg, L0, tid); stage_half(Vg + (size_t)128 * 1024, L1, tid);
	v_mfma_f32_32x32x16_bf16 v[64:79], v[236:239], v[112:115], 0
	ds_read_b128 v[236:239], v189 offset:33888
	s_waitcnt lgkmcnt(2)
	v_mfma_f32_32x32x16_bf16 v[64:79], v[240:243], v[184:187], v[64:79]
	ds_read_b128 v[240:243], v189 offset:33920
	s_waitcnt lgkmcnt(2)
	v_mfma_f32_32x32x16_bf16 v[64:79], v[244:247], v[180:183], v[64:79]
	ds_read_b128 v[244:247], v189 offset:33952
	s_waitcnt lgkmcnt(2)
	v_mfma_f32_32x32x16_bf16 v[64:79], v[236:239], v[176:179], v[64:79]
	ds_read_b128 v[236:239], v189 offset:33984
	s_waitcnt lgkmcnt(2)
	v_mfma_f32_32x32x16_bf16 v[64:79], v[240:243], v[172:175], v[64:79]
	ds_read_b128 v[240:243], v189 offset:34016
	s_waitcnt lgkmcnt(2)
	v_mfma_f32_32x32x16_bf16 v[64:79], v[244:247], v[168:171], v[64:79]
	ds_read_b128 v[244:247], v189 offset:34048
	s_waitcnt lgkmcnt(2)
	v_mfma_f32_32x32x16_bf16 v[64:79], v[236:239], v[164:167], v[64:79]
	ds_read_b128 v[236:239], v189 offset:34080
	s_waitcnt lgkmcnt(2)
	v_mfma_f32_32x32x16_bf16 v[64:79], v[240:243], v[160:163], v[64:79]
	ds_read_b128 v[240:243], v189 offset:34112
	s_waitcnt lgkmcnt(2)
	v_mfma_f32_32x32x16_bf16 v[64:79], v[244:247], v[156:159], v[64:79]
	ds_read_b128 v[244:247], v189 offset:34144
	s_waitcnt lgkmcnt(2)
	v_mfma_f32_32x32x16_bf16 v[64:79], v[236:239], v[152:155], v[64:79]
	ds_read_b128 v[236:239], v189 offset:34176
	s_waitcnt lgkmcnt(2)
	v_mfma_f32_32x32x16_bf16 v[64:79], v[240:243], v[148:151], v[64:79]
	ds_read_b128 v[240:243], v189 offset:34208
	s_waitcnt lgkmcnt(2)
	v_mfma_f32_32x32x16_bf16 v[64:79], v[244:247], v[144:147], v[64:79]
	ds_read_b128 v[244:247], v189 offset:34240
	s_waitcnt lgkmcnt(2)
	v_mfma_f32_32x32x16_bf16 v[64:79], v[236:239], v[140:143], v[64:79]
	ds_read_b128 v[236:239], v189 offset:34272
	s_waitcnt lgkmcnt(2)
	v_mfma_f32_32x32x16_bf16 v[64:79], v[240:243], v[136:139], v[64:79]
	ds_read_b128 v[240:243], v189 offset:50688
	s_waitcnt lgkmcnt(2)
	v_mfma_f32_32x32x16_bf16 v[64:79], v[244:247], v[132:135], v[64:79]
	ds_read_b128 v[244:247], v189 offset:50720
	s_waitcnt lgkmcnt(2)
	v_mfma_f32_32x32x16_bf16 v[64:79], v[236:239], v[128:131], v[64:79]
	ds_read_b128 v[236:239], v189 offset:50752
	s_waitcnt lgkmcnt(2)
	v_mfma_f32_32x32x16_bf16 v[112:127], v[240:243], v[112:115], 0
	ds_read_b128 v[240:243], v189 offset:50784
	s_waitcnt lgkmcnt(2)
	v_mfma_f32_32x32x16_bf16 v[112:127], v[244:247], v[184:187], v[112:127]
	ds_read_b128 v[244:247], v189 offset:50816
	s_waitcnt lgkmcnt(2)
	v_mfma_f32_32x32x16_bf16 v[112:127], v[236:239], v[180:183], v[112:127]
	ds_read_b128 v[236:239], v189 offset:50848
	s_waitcnt lgkmcnt(2)
	v_mfma_f32_32x32x16_bf16 v[112:127], v[240:243], v[176:179], v[112:127]
	ds_read_b128 v[240:243], v189 offset:50880
	s_waitcnt lgkmcnt(2)
	v_mfma_f32_32x32x16_bf16 v[112:127], v[244:247], v[172:175], v[112:127]
	ds_read_b128 v[244:247], v189 offset:50912
	s_waitcnt lgkmcnt(2)
	v_mfma_f32_32x32x16_bf16 v[112:127], v[236:239], v[168:171], v[112:127]
	ds_read_b128 v[236:239], v189 offset:50944
	s_waitcnt lgkmcnt(2)
	v_mfma_f32_32x32x16_bf16 v[112:127], v[240:243], v[164:167], v[112:127]
	ds_read_b128 v[240:243], v189 offset:50976
	s_waitcnt lgkmcnt(2)
	v_mfma_f32_32x32x16_bf16 v[112:127], v[244:247], v[160:163], v[112:127]
	ds_read_b128 v[244:247], v189 offset:51008
	s_waitcnt lgkmcnt(2)
	v_mfma_f32_32x32x16_bf16 v[112:127], v[236:239], v[156:159], v[112:127]
	v_lshl_add_u64 v[160:161], s[16:17], 0, v[190:191]
	ds_read_b128 v[236:239], v189 offset:51040
	s_waitcnt lgkmcnt(2)
	v_mfma_f32_32x32x16_bf16 v[112:127], v[240:243], v[152:155], v[112:127]
	v_lshl_add_u64 v[156:157], v[160:161], 0, s[14:15]
	s_mov_b64 s[14:15], 0x5840000
	ds_read_b128 v[240:243], v189 offset:51072
	s_waitcnt lgkmcnt(2)
	v_mfma_f32_32x32x16_bf16 v[112:127], v[244:247], v[148:151], v[112:127]
	v_lshl_add_u64 v[152:153], v[156:157], 0, v[204:205]
	ds_read_b128 v[244:247], v189 offset:51104
	s_waitcnt lgkmcnt(2)
	v_mfma_f32_32x32x16_bf16 v[112:127], v[236:239], v[144:147], v[112:127]
	v_lshl_add_u64 v[148:149], v[156:157], 0, v[202:203]
	ds_read_b128 v[236:239], v189 offset:51136
	s_waitcnt lgkmcnt(2)
	v_mfma_f32_32x32x16_bf16 v[112:127], v[240:243], v[140:143], v[112:127]
	v_lshl_add_u64 v[144:145], v[156:157], 0, v[200:201]
	ds_read_b128 v[240:243], v189 offset:51168
	s_waitcnt lgkmcnt(2)
	v_mfma_f32_32x32x16_bf16 v[112:127], v[244:247], v[136:139], v[112:127]
	v_lshl_add_u64 v[140:141], v[156:157], 0, v[198:199]
	s_waitcnt lgkmcnt(1)
	v_mfma_f32_32x32x16_bf16 v[112:127], v[236:239], v[132:135], v[112:127]
	s_waitcnt lgkmcnt(0)
	s_barrier
; #define LAS __attribute__((address_space(3)))
; __device__ __forceinline__ void stage_half(const bf16* g, LAS bf16* dst, int tid) {
;     v4u t[8];
; #pragma unroll
;     for (int i = 0; i < 8; ++i) { const int ch = tid + i * NT, r = ch >> 5, cc = ch & 31; t[i] = *(const v4u*)(g + (size_t)r * 1024 + cc * 8); }
; #pragma unroll
;     for (int i = 0; i < 8; ++i) { const int ch = tid + i * NT, r = ch >> 5, cc = ch & 31; *(LAS v4u*)(dst + r * XP + cc * 8) = t[i]; }
; }
; __device__ __forceinline__ void xattn_core(unsigned char* ws, LAS unsigned char* lds, int b, int hd, int qb, int tid, const bf16x8 (&qf)[16]) {
;     ...
;     __syncthreads();
;     stage_half(Vg, L0, tid); stage_half(Vg + (size_t)128 * 1024, L1, tid);
;     float mx = -3.0e38f;
; #pragma unroll
;     for (int mt = 0; mt < 8; ++mt)
; #pragma unroll
;         for (int r = 0; r < 16; ++r) mx = fmaxf(mx, sacc[mt][r]);
;     mx = fmaxf(mx, __shfl_xor(mx, 32));
	v_lshl_add_u64 v[136:137], v[156:157], 0, v[196:197]
	global_load_dwordx4 v[136:139], v[136:137], off
	v_mov_b32_e32 v189, v191
	s_waitcnt lgkmcnt(0)
	v_mfma_f32_32x32x16_bf16 v[112:127], v[240:243], v[128:131], v[112:127]
	v_lshl_add_u64 v[128:129], v[156:157], 0, v[192:193]
	global_load_dwordx4 v[128:131], v[128:129], off
	v_lshl_add_u64 v[132:133], v[156:157], 0, v[194:195]
	global_load_dwordx4 v[132:135], v[132:133], off
	v_lshl_add_u64 v[156:157], v[156:157], 0, v[206:207]
	global_load_dwordx4 v[140:143], v[140:141], off
	s_nop 0
	global_load_dwordx4 v[144:147], v[144:145], off
	s_nop 0
	global_load_dwordx4 v[148:151], v[148:149], off
	s_nop 0
	global_load_dwordx4 v[152:155], v[152:153], off
	s_nop 0
	global_load_dwordx4 v[156:159], v[156:157], off
	s_waitcnt vmcnt(6)
	ds_write_b128 v223, v[128:131]
	s_waitcnt vmcnt(5)
	ds_write_b128 v222, v[132:135]
	ds_write_b128 v221, v[136:139]
	s_waitcnt vmcnt(4)
	ds_write_b128 v220, v[140:143]
	s_waitcnt vmcnt(3)
	ds_write_b128 v219, v[144:147]
	s_waitcnt vmcnt(2)
	ds_write_b128 v218, v[148:151]
	s_waitcnt vmcnt(1)
	ds_write_b128 v217, v[152:155]
	s_waitcnt vmcnt(0)
	ds_write_b128 v216, v[156:159]
	v_lshl_add_u64 v[156:157], v[160:161], 0, s[14:15]
	v_lshl_add_u64 v[128:129], v[156:157], 0, v[192:193]
	global_load_dwordx4 v[128:131], v[128:129], off
	v_lshl_add_u64 v[132:133], v[156:157], 0, v[194:195]
	global_load_dwordx4 v[132:135], v[132:133], off
	v_lshl_add_u64 v[136:137], v[156:157], 0, v[196:197]
	global_load_dwordx4 v[136:139], v[136:137], off
	v_lshl_add_u64 v[140:141], v[156:157], 0, v[198:199]
	global_load_dwordx4 v[140:143], v[140:141], off
	v_lshl_add_u64 v[144:145], v[156:157], 0, v[200:201]
	global_load_dwordx4 v[144:147], v[144:145], off
	v_lshl_add_u64 v[148:149], v[156:157], 0, v[202:203]
	global_load_dwordx4 v[148:151], v[148:149], off
	v_lshl_add_u64 v[152:153], v[156:157], 0, v[204:205]
	global_load_dwordx4 v[152:155], v[152:153], off
	v_lshl_add_u64 v[156:157], v[156:157], 0, v[206:207]
	global_load_dwordx4 v[156:159], v[156:157], off
	s_waitcnt vmcnt(7)
	ds_write_b128 v230, v[128:131]
	s_waitcnt vmcnt(6)
	ds_write_b128 v224, v[132:135]
	s_waitcnt vmcnt(5)
	ds_write_b128 v225, v[136:139]
	s_waitcnt vmcnt(4)
	ds_write_b128 v226, v[140:143]
	s_waitcnt vmcnt(3)
	ds_write_b128 v227, v[144:147]
	s_waitcnt vmcnt(2)
	ds_write_b128 v228, v[148:151]
	s_waitcnt vmcnt(1)
	ds_write_b128 v229, v[152:155]
	s_waitcnt vmcnt(0)
	ds_write_b128 v215, v[156:159]
	v_max3_f32 v128, v96, s7, v97
	v_max3_f32 v128, v128, v98, v99
	v_max3_f32 v128, v128, v100, v101
	v_max3_f32 v128, v128, v102, v103
	v_max3_f32 v128, v128, v104, v105
	v_max3_f32 v128, v128, v106, v107
	v_max3_f32 v128, v128, v108, v109
	v_max3_f32 v128, v128, v110, v111
	v_max3_f32 v128, v128, v32, v33
	v_max3_f32 v128, v128, v34, v35
	v_max3_f32 v128, v128, v36, v37
	v_max3_f32 v128, v128, v38, v39
	v_max3_f32 v128, v128, v40, v41
	v_max3_f32 v128, v128, v42, v43
	v_max3_f32 v128, v128, v44, v45
	v_max3_f32 v128, v128, v46, v47
	v_max3_f32 v128, v128, v16, v17
	v_max3_f32 v128, v128, v18, v19
	v_max3_f32 v128, v128, v20, v21
	v_max3_f32 v128, v128, v22, v23
	v_max3_f32 v128, v128, v24, v25
	v_max3_f32 v128, v128, v26, v27
	v_max3_f32 v128, v128, v28, v29
	v_max3_f32 v128, v128, v30, v31
	v_max3_f32 v128, v128, v0, v1
	v_max3_f32 v128, v128, v2, v3
	v_max3_f32 v128, v128, v4, v5
	v_max3_f32 v128, v128, v6, v7
	v_max3_f32 v128, v128, v8, v9
	v_max3_f32 v128, v128, v10, v11
	v_max3_f32 v128, v128, v12, v13
	v_max3_f32 v128, v128, v14, v15
	v_max3_f32 v128, v128, v48, v49
	v_max3_f32 v128, v128, v50, v51
	v_max3_f32 v128, v128, v52, v53
	v_max3_f32 v128, v128, v54, v55
	v_max3_f32 v128, v128, v56, v57
	v_max3_f32 v128, v128, v58, v59
	v_max3_f32 v128, v128, v60, v61
	v_max3_f32 v128, v128, v62, v63
	v_max3_f32 v128, v128, v80, v81
	v_max3_f32 v128, v128, v82, v83
	v_max3_f32 v128, v128, v84, v85
	v_max3_f32 v128, v128, v86, v87
	v_max3_f32 v128, v128, v88, v89
	v_max3_f32 v128, v128, v90, v91
	v_max3_f32 v128, v128, v92, v93
	v_max3_f32 v128, v128, v94, v95
	v_max3_f32 v128, v128, v64, v65
	v_max3_f32 v128, v128, v66, v67
	v_max3_f32 v128, v128, v68, v69
	v_max3_f32 v128, v128, v70, v71
	v_max3_f32 v128, v128, v72, v73
	v_max3_f32 v128, v128, v74, v75
	v_max3_f32 v128, v128, v76, v77
	v_max3_f32 v128, v128, v78, v79
	v_max3_f32 v128, v128, v112, v113
	v_max3_f32 v128, v128, v114, v115
	v_max3_f32 v128, v128, v116, v117
	v_max3_f32 v128, v128, v118, v119
	v_max3_f32 v128, v128, v120, v121
	v_max3_f32 v128, v128, v122, v123
	v_max3_f32 v128, v128, v124, v125
	v_max3_f32 v129, v128, v126, v127
	v_mbcnt_lo_u32_b32 v128, -1, 0
	v_mbcnt_hi_u32_b32 v128, -1, v128
	v_and_b32_e32 v131, 64, v128
	v_xor_b32_e32 v130, 32, v128
	v_add_u32_e32 v131, 64, v131
	v_cmp_lt_i32_e32 vcc, v130, v131
	s_waitcnt lgkmcnt(0)
	s_barrier
; __device__ __forceinline__ unsigned pk2(float lo, float hi) { return pg8::cvt_pk_bf16(lo, hi); }
; __device__ __forceinline__ void xattn_core(unsigned char* ws, LAS unsigned char* lds, int b, int hd, int qb, int tid, const bf16x8 (&qf)[16]) {
;     ...
;     mx = fmaxf(mx, __shfl_xor(mx, 32));
;     float sum = 0.f; bf16x8 pf[8][2];
; #pragma unroll
;     for (int mt = 0; mt < 8; ++mt) {
;         float e[16];
; #pragma unroll
;         for (int r = 0; r < 16; ++r) { e[r] = __expf(sacc[mt][r] - mx); sum += e[r]; }
; #pragma unroll
;         for (int s = 0; s < 2; ++s) { v4u w; w.x = pk2(e[8 * s], e[8 * s + 1]); w.y = pk2(e[8 * s + 2], e[8 * s + 3]); w.z = pk2(e[8 * s + 4], e[8 * s + 5]); w.w = pk2(e[8 * s + 6], e[8 * s + 7]); pf[mt][s] = __builtin_bit_cast(bf16x8, w); }
	v_cndmask_b32_e32 v128, v128, v130, vcc
	v_lshlrev_b32_e32 v128, 2, v128
	ds_bpermute_b32 v130, v128, v129
	s_waitcnt lgkmcnt(0)
	v_max_f32_e32 v130, v130, v130
	v_max_f32_e32 v129, v129, v130
	v_mov_b32_e32 v184, 0x3fb8aa3b
	v_mul_f32_e32 v185, 0xbfb8aa3b, v129
	v_fma_f32 v96, v96, v184, v185
	v_exp_f32_e32 v130, v96
	v_fma_f32 v96, v97, v184, v185
	v_exp_f32_e32 v131, v96
	v_fma_f32 v96, v98, v184, v185
	v_exp_f32_e32 v132, v96
	v_fma_f32 v96, v99, v184, v185
	v_exp_f32_e32 v133, v96
	v_fma_f32 v96, v100, v184, v185
	v_exp_f32_e32 v134, v96
	v_fma_f32 v96, v101, v184, v185
	v_exp_f32_e32 v135, v96
	v_fma_f32 v96, v102, v184, v185
	v_exp_f32_e32 v136, v96
	v_fma_f32 v96, v103, v184, v185
	v_exp_f32_e32 v137, v96
	v_fma_f32 v96, v104, v184, v185
	v_exp_f32_e32 v104, v96
	v_fma_f32 v96, v105, v184, v185
	v_exp_f32_e32 v105, v96
	v_fma_f32 v96, v106, v184, v185
	v_exp_f32_e32 v106, v96
	v_fma_f32 v96, v107, v184, v185
	v_exp_f32_e32 v107, v96
	v_fma_f32 v96, v108, v184, v185
	v_exp_f32_e32 v108, v96
	v_fma_f32 v96, v109, v184, v185
	v_exp_f32_e32 v109, v96
	v_fma_f32 v96, v110, v184, v185
	v_exp_f32_e32 v110, v96
	v_fma_f32 v96, v111, v184, v185
	v_exp_f32_e32 v111, v96
	v_cvt_pk_bf16_f32 v96, v130, v131
	v_add_f32_e32 v130, 0, v130
	v_add_f32_e32 v130, v131, v130
	v_add_f32_e32 v130, v132, v130
	v_add_f32_e32 v130, v133, v130
	v_add_f32_e32 v130, v134, v130
	v_add_f32_e32 v130, v135, v130
	v_add_f32_e32 v130, v136, v130
	v_add_f32_e32 v130, v137, v130
	v_fma_f32 v32, v32, v184, v185
	v_cvt_pk_bf16_f32 v100, v104, v105
	v_add_f32_e32 v104, v104, v130
	v_add_f32_e32 v104, v105, v104
	v_exp_f32_e32 v105, v32
	v_fma_f32 v32, v33, v184, v185
	v_cvt_pk_bf16_f32 v101, v106, v107
	v_add_f32_e32 v104, v106, v104
	v_exp_f32_e32 v106, v32
	v_fma_f32 v32, v34, v184, v185
	v_add_f32_e32 v104, v107, v104
	v_exp_f32_e32 v107, v32
	v_fma_f32 v32, v35, v184, v185
	v_cvt_pk_bf16_f32 v102, v108, v109
	v_add_f32_e32 v104, v108, v104
	v_exp_f32_e32 v108, v32
	v_fma_f32 v32, v36, v184, v185
	v_add_f32_e32 v104, v109, v104
	v_exp_f32_e32 v109, v32
	v_fma_f32 v32, v37, v184, v185
	v_cvt_pk_bf16_f32 v103, v110, v111
	v_add_f32_e32 v104, v110, v104
	v_exp_f32_e32 v110, v32
	v_fma_f32 v32, v38, v184, v185
	v_add_f32_e32 v104, v111, v104
	v_exp_f32_e32 v111, v32
	v_fma_f32 v32, v39, v184, v185
	v_exp_f32_e32 v130, v32
	v_fma_f32 v32, v40, v184, v185
	v_add_f32_e32 v104, v105, v104
	v_exp_f32_e32 v40, v32
	v_fma_f32 v32, v41, v184, v185
	v_add_f32_e32 v104, v106, v104
	v_add_f32_e32 v104, v107, v104
	v_exp_f32_e32 v41, v32
	v_fma_f32 v32, v42, v184, v185
	v_add_f32_e32 v104, v108, v104
	v_add_f32_e32 v104, v109, v104
	v_exp_f32_e32 v42, v32
	v_fma_f32 v32, v43, v184, v185
	v_add_f32_e32 v104, v110, v104
	v_add_f32_e32 v104, v111, v104
	v_exp_f32_e32 v43, v32
	v_fma_f32 v32, v44, v184, v185
	v_add_f32_e32 v104, v130, v104
	v_fma_f32 v16, v16, v184, v185
	v_cvt_pk_bf16_f32 v36, v40, v41
	v_add_f32_e32 v40, v40, v104
	v_exp_f32_e32 v44, v32
	v_fma_f32 v32, v45, v184, v185
	v_add_f32_e32 v40, v41, v40
	v_exp_f32_e32 v41, v16
	v_fma_f32 v16, v17, v184, v185
	v_exp_f32_e32 v45, v32
	v_fma_f32 v32, v46, v184, v185
	v_cvt_pk_bf16_f32 v37, v42, v43
	v_add_f32_e32 v40, v42, v40
	v_exp_f32_e32 v42, v16
	v_fma_f32 v16, v18, v184, v185
	v_exp_f32_e32 v46, v32
	v_fma_f32 v32, v47, v184, v185
	v_add_f32_e32 v40, v43, v40
	v_exp_f32_e32 v43, v16
	v_fma_f32 v16, v19, v184, v185
	v_exp_f32_e32 v47, v32
	v_cvt_pk_bf16_f32 v38, v44, v45
	v_add_f32_e32 v40, v44, v40
	v_exp_f32_e32 v44, v16
	v_fma_f32 v16, v20, v184, v185
	v_add_f32_e32 v40, v45, v40
	v_exp_f32_e32 v45, v16
	v_fma_f32 v16, v21, v184, v185
	v_cvt_pk_bf16_f32 v39, v46, v47
	v_add_f32_e32 v40, v46, v40
	v_exp_f32_e32 v46, v16
	v_fma_f32 v16, v22, v184, v185
	v_add_f32_e32 v40, v47, v40
	v_exp_f32_e32 v47, v16
	v_fma_f32 v16, v23, v184, v185
	v_exp_f32_e32 v104, v16
	v_fma_f32 v16, v24, v184, v185
	v_exp_f32_e32 v24, v16
	v_fma_f32 v16, v25, v184, v185
	v_exp_f32_e32 v25, v16
	v_fma_f32 v16, v26, v184, v185
	v_add_f32_e32 v40, v41, v40
	v_exp_f32_e32 v26, v16
	v_fma_f32 v16, v27, v184, v185
	v_add_f32_e32 v40, v42, v40
	v_add_f32_e32 v40, v43, v40
	v_exp_f32_e32 v27, v16
	v_fma_f32 v16, v28, v184, v185
	v_add_f32_e32 v40, v44, v40
	v_add_f32_e32 v40, v45, v40
	v_exp_f32_e32 v28, v16
	v_fma_f32 v16, v29, v184, v185
	v_add_f32_e32 v40, v46, v40
	v_add_f32_e32 v40, v47, v40
	v_exp_f32_e32 v29, v16
	v_fma_f32 v16, v30, v184, v185
	v_add_f32_e32 v40, v104, v40
	v_cvt_pk_bf16_f32 v20, v24, v25
	v_add_f32_e32 v24, v24, v40
	v_exp_f32_e32 v30, v16
	v_fma_f32 v16, v31, v184, v185
	v_add_f32_e32 v24, v25, v24
	v_add_f32_e32 v24, v26, v24
	v_fma_f32 v0, v0, v184, v185
	v_fma_f32 v1, v1, v184, v185
	v_exp_f32_e32 v31, v16
	v_add_f32_e32 v24, v27, v24
	v_add_f32_e32 v24, v28, v24
	v_exp_f32_e32 v0, v0
	v_exp_f32_e32 v1, v1
	v_fma_f32 v2, v2, v184, v185
	v_add_f32_e32 v24, v29, v24
	v_fma_f32 v3, v3, v184, v185
	v_add_f32_e32 v24, v30, v24
	v_exp_f32_e32 v2, v2
	v_fma_f32 v4, v4, v184, v185
	v_add_f32_e32 v40, v31, v24
	v_exp_f32_e32 v3, v3
	v_fma_f32 v5, v5, v184, v185
	v_exp_f32_e32 v4, v4
	v_fma_f32 v6, v6, v184, v185
	v_cvt_pk_bf16_f32 v24, v0, v1
	v_add_f32_e32 v0, v0, v40
	v_exp_f32_e32 v5, v5
	v_fma_f32 v7, v7, v184, v185
	v_add_f32_e32 v0, v1, v0
	v_exp_f32_e32 v6, v6
	v_fma_f32 v8, v8, v184, v185
	v_add_f32_e32 v0, v2, v0
	v_exp_f32_e32 v7, v7
	v_fma_f32 v9, v9, v184, v185
	v_add_f32_e32 v0, v3, v0
	v_exp_f32_e32 v8, v8
	v_fma_f32 v10, v10, v184, v185
	v_add_f32_e32 v0, v4, v0
	v_exp_f32_e32 v9, v9
	v_fma_f32 v11, v11, v184, v185
	v_add_f32_e32 v0, v5, v0
	v_exp_f32_e32 v10, v10
	v_fma_f32 v12, v12, v184, v185
	v_add_f32_e32 v0, v6, v0
; __device__ __forceinline__ unsigned pk2(float lo, float hi) { return pg8::cvt_pk_bf16(lo, hi); }
; __device__ __forceinline__ void xattn_core(unsigned char* ws, LAS unsigned char* lds, int b, int hd, int qb, int tid, const bf16x8 (&qf)[16]) {
;     ...
;     float sum = 0.f; bf16x8 pf[8][2];
; #pragma unroll
;     for (int mt = 0; mt < 8; ++mt) {
;         float e[16];
; #pragma unroll
;         for (int r = 0; r < 16; ++r) { e[r] = __expf(sacc[mt][r] - mx); sum += e[r]; }
; #pragma unroll
;         for (int s = 0; s < 2; ++s) { v4u w; w.x = pk2(e[8 * s], e[8 * s + 1]); w.y = pk2(e[8 * s + 2], e[8 * s + 3]); w.z = pk2(e[8 * s + 4], e[8 * s + 5]); w.w = pk2(e[8 * s + 6], e[8 * s + 7]); pf[mt][s] = __builtin_bit_cast(bf16x8, w); }
;     }
	v_exp_f32_e32 v11, v11
	v_fma_f32 v13, v13, v184, v185
	v_add_f32_e32 v0, v7, v0
	v_exp_f32_e32 v12, v12
	v_fma_f32 v14, v14, v184, v185
	v_add_f32_e32 v0, v8, v0
	v_exp_f32_e32 v13, v13
	v_fma_f32 v15, v15, v184, v185
	v_add_f32_e32 v0, v9, v0
	v_exp_f32_e32 v14, v14
	v_add_f32_e32 v0, v10, v0
	v_fma_f32 v1, v48, v184, v185
	v_exp_f32_e32 v15, v15
	v_cvt_pk_bf16_f32 v25, v2, v3
	v_add_f32_e32 v0, v11, v0
	v_fma_f32 v2, v49, v184, v185
	v_add_f32_e32 v0, v12, v0
	v_exp_f32_e32 v1, v1
	v_fma_f32 v3, v50, v184, v185
	v_cvt_pk_bf16_f32 v21, v26, v27
	v_cvt_pk_bf16_f32 v26, v4, v5
	v_add_f32_e32 v0, v13, v0
	v_exp_f32_e32 v2, v2
	v_fma_f32 v4, v51, v184, v185
	v_add_f32_e32 v0, v14, v0
	v_exp_f32_e32 v3, v3
	v_fma_f32 v5, v52, v184, v185
	v_cvt_pk_bf16_f32 v27, v6, v7
	v_add_f32_e32 v0, v15, v0
	v_exp_f32_e32 v4, v4
	v_fma_f32 v6, v53, v184, v185
	v_exp_f32_e32 v5, v5
	v_fma_f32 v7, v54, v184, v185
	v_add_f32_e32 v0, v1, v0
	v_cvt_pk_bf16_f32 v22, v28, v29
	v_cvt_pk_bf16_f32 v28, v8, v9
	v_exp_f32_e32 v6, v6
	v_fma_f32 v8, v55, v184, v185
	v_add_f32_e32 v0, v2, v0
	v_exp_f32_e32 v7, v7
	v_fma_f32 v9, v56, v184, v185
	v_add_f32_e32 v0, v3, v0
	v_cvt_pk_bf16_f32 v29, v10, v11
	v_exp_f32_e32 v8, v8
	v_fma_f32 v10, v57, v184, v185
	v_add_f32_e32 v0, v4, v0
	v_exp_f32_e32 v9, v9
	v_fma_f32 v11, v58, v184, v185
	v_add_f32_e32 v0, v5, v0
	v_cvt_pk_bf16_f32 v23, v30, v31
	v_cvt_pk_bf16_f32 v30, v12, v13
	v_exp_f32_e32 v10, v10
	v_fma_f32 v12, v59, v184, v185
	v_add_f32_e32 v0, v6, v0
	v_exp_f32_e32 v11, v11
	v_fma_f32 v13, v60, v184, v185
	v_add_f32_e32 v0, v7, v0
	v_cvt_pk_bf16_f32 v31, v14, v15
	v_exp_f32_e32 v12, v12
	v_fma_f32 v14, v61, v184, v185
	v_add_f32_e32 v0, v8, v0
	v_exp_f32_e32 v13, v13
	v_fma_f32 v15, v62, v184, v185
	v_fma_f32 v40, v63, v184, v185
	v_add_f32_e32 v0, v9, v0
	v_exp_f32_e32 v14, v14
	v_add_f32_e32 v0, v10, v0
	v_exp_f32_e32 v15, v15
	v_exp_f32_e32 v48, v40
	v_cvt_pk_bf16_f32 v40, v1, v2
	v_add_f32_e32 v0, v11, v0
	v_fma_f32 v1, v80, v184, v185
	v_add_f32_e32 v0, v12, v0
	v_fma_f32 v2, v81, v184, v185
	v_cvt_pk_bf16_f32 v16, v41, v42
	v_cvt_pk_bf16_f32 v41, v3, v4
	v_add_f32_e32 v0, v13, v0
	v_exp_f32_e32 v1, v1
	v_fma_f32 v3, v82, v184, v185
	v_add_f32_e32 v0, v14, v0
	v_exp_f32_e32 v2, v2
	v_fma_f32 v4, v83, v184, v185
	v_cvt_pk_bf16_f32 v42, v5, v6
	v_add_f32_e32 v0, v15, v0
	v_exp_f32_e32 v3, v3
	v_fma_f32 v5, v84, v184, v185
	v_add_f32_e32 v0, v48, v0
	v_exp_f32_e32 v4, v4
	v_fma_f32 v6, v85, v184, v185
	v_cvt_pk_bf16_f32 v17, v43, v44
	v_cvt_pk_bf16_f32 v43, v7, v8
	v_exp_f32_e32 v5, v5
	v_fma_f32 v7, v86, v184, v185
	v_add_f32_e32 v0, v1, v0
	v_exp_f32_e32 v6, v6
	v_fma_f32 v8, v87, v184, v185
	v_add_f32_e32 v0, v2, v0
	v_cvt_pk_bf16_f32 v44, v9, v10
	v_exp_f32_e32 v7, v7
	v_fma_f32 v9, v88, v184, v185
	v_add_f32_e32 v0, v3, v0
	v_exp_f32_e32 v8, v8
	v_fma_f32 v10, v89, v184, v185
	v_add_f32_e32 v0, v4, v0
	v_cvt_pk_bf16_f32 v18, v45, v46
	v_cvt_pk_bf16_f32 v45, v11, v12
	v_exp_f32_e32 v9, v9
	v_fma_f32 v11, v90, v184, v185
	v_add_f32_e32 v0, v5, v0
	v_exp_f32_e32 v10, v10
	v_fma_f32 v12, v91, v184, v185
	v_add_f32_e32 v0, v6, v0
	v_cvt_pk_bf16_f32 v46, v13, v14
	v_exp_f32_e32 v11, v11
	v_fma_f32 v13, v92, v184, v185
	v_add_f32_e32 v0, v7, v0
	v_exp_f32_e32 v12, v12
	v_fma_f32 v14, v93, v184, v185
	v_add_f32_e32 v0, v8, v0
	v_cvt_pk_bf16_f32 v19, v47, v104
	v_cvt_pk_bf16_f32 v47, v15, v48
	v_exp_f32_e32 v13, v13
	v_fma_f32 v15, v94, v184, v185
	v_fma_f32 v48, v95, v184, v185
	v_add_f32_e32 v0, v9, v0
	v_exp_f32_e32 v14, v14
	v_add_f32_e32 v0, v10, v0
	v_exp_f32_e32 v15, v15
	v_exp_f32_e32 v56, v48
	v_cvt_pk_bf16_f32 v48, v1, v2
	v_add_f32_e32 v0, v11, v0
	v_fma_f32 v1, v64, v184, v185
	v_add_f32_e32 v0, v12, v0
	v_fma_f32 v2, v65, v184, v185
	v_cvt_pk_bf16_f32 v49, v3, v4
	v_add_f32_e32 v0, v13, v0
	v_exp_f32_e32 v1, v1
	v_fma_f32 v3, v66, v184, v185
	v_add_f32_e32 v0, v14, v0
	v_exp_f32_e32 v2, v2
	v_fma_f32 v4, v67, v184, v185
	v_cvt_pk_bf16_f32 v50, v5, v6
	v_add_f32_e32 v0, v15, v0
	v_exp_f32_e32 v3, v3
	v_fma_f32 v5, v68, v184, v185
	v_add_f32_e32 v0, v56, v0
; __device__ __forceinline__ unsigned pk2(float lo, float hi) { return pg8::cvt_pk_bf16(lo, hi); }
; __device__ __forceinline__ void xattn_core(unsigned char* ws, LAS unsigned char* lds, int b, int hd, int qb, int tid, const bf16x8 (&qf)[16]) {
;     ...
;     float sum = 0.f; bf16x8 pf[8][2];
; #pragma unroll
;     for (int mt = 0; mt < 8; ++mt) {
;         float e[16];
; #pragma unroll
;         for (int r = 0; r < 16; ++r) { e[r] = __expf(sacc[mt][r] - mx); sum += e[r]; }
; #pragma unroll
;         for (int s = 0; s < 2; ++s) { v4u w; w.x = pk2(e[8 * s], e[8 * s + 1]); w.y = pk2(e[8 * s + 2], e[8 * s + 3]); w.z = pk2(e[8 * s + 4], e[8 * s + 5]); w.w = pk2(e[8 * s + 6], e[8 * s + 7]); pf[mt][s] = __builtin_bit_cast(bf16x8, w); }
;     }
;     sum += __shfl_xor(sum, 32);
;     const float inv = 1.f / sum;
;     __syncthreads();
;     bf16* op = (bf16*)(ws + WS_O) + (size_t)(q0 + r32) * 1024 + hd * 256 + 4 * hh;
	v_exp_f32_e32 v4, v4
	v_fma_f32 v6, v69, v184, v185
	v_cvt_pk_bf16_f32 v51, v7, v8
	v_exp_f32_e32 v5, v5
	v_fma_f32 v7, v70, v184, v185
	v_add_f32_e32 v0, v1, v0
	v_exp_f32_e32 v6, v6
	v_fma_f32 v8, v71, v184, v185
	v_add_f32_e32 v0, v2, v0
	v_cvt_pk_bf16_f32 v52, v9, v10
	v_exp_f32_e32 v7, v7
	v_fma_f32 v9, v72, v184, v185
	v_add_f32_e32 v0, v3, v0
	v_exp_f32_e32 v8, v8
	v_fma_f32 v10, v73, v184, v185
	v_add_f32_e32 v0, v4, v0
	v_cvt_pk_bf16_f32 v53, v11, v12
	v_exp_f32_e32 v9, v9
	v_fma_f32 v11, v74, v184, v185
	v_add_f32_e32 v0, v5, v0
	v_exp_f32_e32 v10, v10
	v_fma_f32 v12, v75, v184, v185
	v_add_f32_e32 v0, v6, v0
	v_cvt_pk_bf16_f32 v54, v13, v14
	v_exp_f32_e32 v11, v11
	v_fma_f32 v13, v76, v184, v185
	v_add_f32_e32 v0, v7, v0
	v_exp_f32_e32 v12, v12
	v_fma_f32 v14, v77, v184, v185
	v_add_f32_e32 v0, v8, v0
	v_cvt_pk_bf16_f32 v55, v15, v56
	v_exp_f32_e32 v13, v13
	v_fma_f32 v15, v78, v184, v185
	v_fma_f32 v56, v79, v184, v185
	v_add_f32_e32 v0, v9, v0
	v_exp_f32_e32 v14, v14
	v_add_f32_e32 v0, v10, v0
	v_exp_f32_e32 v15, v15
	v_exp_f32_e32 v64, v56
	v_cvt_pk_bf16_f32 v56, v1, v2
	v_add_f32_e32 v0, v11, v0
	v_fma_f32 v1, v112, v184, v185
	v_add_f32_e32 v0, v12, v0
	v_fma_f32 v2, v113, v184, v185
	v_cvt_pk_bf16_f32 v57, v3, v4
	v_add_f32_e32 v0, v13, v0
	v_exp_f32_e32 v1, v1
	v_fma_f32 v3, v114, v184, v185
	v_add_f32_e32 v0, v14, v0
	v_exp_f32_e32 v2, v2
	v_fma_f32 v4, v115, v184, v185
	v_cvt_pk_bf16_f32 v58, v5, v6
	v_add_f32_e32 v0, v15, v0
	v_exp_f32_e32 v3, v3
	v_fma_f32 v5, v116, v184, v185
	v_add_f32_e32 v0, v64, v0
	v_exp_f32_e32 v4, v4
	v_fma_f32 v6, v117, v184, v185
	v_cvt_pk_bf16_f32 v59, v7, v8
	v_exp_f32_e32 v5, v5
	v_fma_f32 v7, v118, v184, v185
	v_add_f32_e32 v0, v1, v0
	v_exp_f32_e32 v6, v6
	v_fma_f32 v8, v119, v184, v185
	v_add_f32_e32 v0, v2, v0
	v_cvt_pk_bf16_f32 v60, v9, v10
	v_exp_f32_e32 v7, v7
	v_fma_f32 v9, v120, v184, v185
	v_add_f32_e32 v0, v3, v0
	v_exp_f32_e32 v8, v8
	v_fma_f32 v10, v121, v184, v185
	v_add_f32_e32 v0, v4, v0
	v_cvt_pk_bf16_f32 v61, v11, v12
	v_exp_f32_e32 v9, v9
	v_fma_f32 v11, v122, v184, v185
	v_add_f32_e32 v0, v5, v0
	v_exp_f32_e32 v10, v10
	v_fma_f32 v12, v123, v184, v185
	v_add_f32_e32 v0, v6, v0
	v_cvt_pk_bf16_f32 v62, v13, v14
	v_exp_f32_e32 v11, v11
	v_fma_f32 v13, v124, v184, v185
	v_add_f32_e32 v0, v7, v0
	v_exp_f32_e32 v12, v12
	v_fma_f32 v14, v125, v184, v185
	v_add_f32_e32 v0, v8, v0
	v_cvt_pk_bf16_f32 v63, v15, v64
	v_exp_f32_e32 v13, v13
	v_fma_f32 v15, v126, v184, v185
	v_add_f32_e32 v0, v9, v0
	v_exp_f32_e32 v14, v14
	v_fma_f32 v64, v127, v184, v185
	v_add_f32_e32 v0, v10, v0
	v_exp_f32_e32 v15, v15
	v_add_f32_e32 v0, v11, v0
	v_exp_f32_e32 v72, v64
	v_add_f32_e32 v0, v12, v0
	v_add_f32_e32 v0, v13, v0
	v_add_f32_e32 v0, v14, v0
	v_add_f32_e32 v0, v15, v0
	v_add_f32_e32 v0, v72, v0
	v_cvt_pk_bf16_f32 v64, v1, v2
	ds_bpermute_b32 v1, v128, v0
	v_cvt_pk_bf16_f32 v65, v3, v4
	v_cvt_pk_bf16_f32 v66, v5, v6
	v_cvt_pk_bf16_f32 v71, v15, v72
	v_cvt_pk_bf16_f32 v97, v132, v133
	s_waitcnt lgkmcnt(0)
	v_add_f32_e32 v0, v0, v1
	v_div_scale_f32 v1, s[14:15], v0, v0, 1.0
	v_rcp_f32_e32 v2, v1
	v_cvt_pk_bf16_f32 v98, v134, v135
	v_cvt_pk_bf16_f32 v99, v136, v137
	v_cvt_pk_bf16_f32 v32, v105, v106
	v_fma_f32 v3, -v1, v2, 1.0
	v_fmac_f32_e32 v2, v3, v2
	v_div_scale_f32 v3, vcc, 1.0, v0, 1.0
	v_mul_f32_e32 v4, v3, v2
	v_fma_f32 v5, -v1, v4, v3
	v_fmac_f32_e32 v4, v5, v2
	v_fma_f32 v1, -v1, v4, v3
	v_div_fmas_f32 v1, v1, v2, v4
	v_div_fixup_f32 v72, v1, v0, 1.0
	v_add_u32_e32 v0, s6, v214
	v_ashrrev_i32_e32 v1, 31, v0
	v_lshlrev_b64 v[0:1], 11, v[0:1]
	v_lshl_add_u64 v[2:3], s[48:49], 0, v[188:189]
	v_lshl_add_u64 v[0:1], v[0:1], 0, s[4:5]
	v_lshl_add_u64 v[0:1], v[2:3], 0, v[0:1]
	s_mov_b64 s[4:5], 0xc000020
	v_cvt_pk_bf16_f32 v33, v107, v108
	v_cvt_pk_bf16_f32 v34, v109, v110
	v_cvt_pk_bf16_f32 v35, v111, v130
	v_cvt_pk_bf16_f32 v67, v7, v8
	v_cvt_pk_bf16_f32 v68, v9, v10
	v_cvt_pk_bf16_f32 v69, v11, v12
	v_cvt_pk_bf16_f32 v70, v13, v14
	v_mov_b32_e32 v73, v72
	v_lshl_add_u64 v[74:75], v[0:1], 0, s[4:5]
	v_lshlrev_b32_e32 v76, 1, v211
	s_mov_b32 s4, 0
